# attention softmax row sums with packed f32 adds (14 v_pk_add_f32 instead of 32 scalar adds)
# speedup vs baseline: 1.0062x; 1.0062x over previous
.LBB0_738:
	v_exp_f32_e32 v32, v32
	v_exp_f32_e32 v48, v48
	v_exp_f32_e32 v33, v33
	v_exp_f32_e32 v49, v49
	v_exp_f32_e32 v34, v34
	v_exp_f32_e32 v50, v50
	v_exp_f32_e32 v35, v35
	v_exp_f32_e32 v51, v51
	v_pk_add_f32 v[232:233], v[32:33], v[34:35]
	v_exp_f32_e32 v36, v36
	v_exp_f32_e32 v52, v52
	v_pk_add_f32 v[234:235], v[48:49], v[50:51]
	v_exp_f32_e32 v37, v37
	v_exp_f32_e32 v53, v53
	v_exp_f32_e32 v38, v38
	v_exp_f32_e32 v54, v54
	v_pk_add_f32 v[232:233], v[232:233], v[36:37]
	v_exp_f32_e32 v39, v39
	v_exp_f32_e32 v55, v55
	v_pk_add_f32 v[234:235], v[234:235], v[52:53]
	v_exp_f32_e32 v40, v40
	v_exp_f32_e32 v56, v56
	v_exp_f32_e32 v57, v57
	v_pk_add_f32 v[232:233], v[232:233], v[38:39]
	v_cvt_pk_bf16_f32 v67, v34, v35
	v_pk_add_f32 v[234:235], v[234:235], v[54:55]
	v_cvt_pk_bf16_f32 v68, v36, v37
	v_cvt_pk_bf16_f32 v66, v32, v33
	v_cvt_pk_bf16_f32 v69, v38, v39
	v_exp_f32_e32 v41, v41
	v_exp_f32_e32 v42, v42
	v_mfma_f32_32x32x16_bf16 v[0:15], v[108:111], v[66:69], v[0:15]
	v_exp_f32_e32 v43, v43
	v_exp_f32_e32 v44, v44
	v_exp_f32_e32 v45, v45
	v_exp_f32_e32 v46, v46
	v_exp_f32_e32 v47, v47
	v_exp_f32_e32 v58, v58
	v_pk_add_f32 v[232:233], v[232:233], v[40:41]
	v_mfma_f32_32x32x16_bf16 v[16:31], v[124:127], v[66:69], v[16:31]
	v_cvt_pk_bf16_f32 v66, v40, v41
	v_cvt_pk_bf16_f32 v67, v42, v43
	v_cvt_pk_bf16_f32 v68, v44, v45
	v_cvt_pk_bf16_f32 v69, v46, v47
	v_exp_f32_e32 v59, v59
	v_pk_add_f32 v[232:233], v[232:233], v[42:43]
	v_mfma_f32_32x32x16_bf16 v[0:15], v[104:107], v[66:69], v[0:15]
	v_pk_add_f32 v[234:235], v[234:235], v[56:57]
	v_exp_f32_e32 v60, v60
	v_exp_f32_e32 v61, v61
	v_exp_f32_e32 v62, v62
	v_exp_f32_e32 v63, v63
	v_mfma_f32_32x32x16_bf16 v[16:31], v[120:123], v[66:69], v[16:31]
	v_cvt_pk_bf16_f32 v66, v48, v49
	v_cvt_pk_bf16_f32 v67, v50, v51
	v_cvt_pk_bf16_f32 v68, v52, v53
	v_cvt_pk_bf16_f32 v69, v54, v55
	v_pk_add_f32 v[232:233], v[232:233], v[44:45]
	v_pk_add_f32 v[234:235], v[234:235], v[58:59]
	v_mfma_f32_32x32x16_bf16 v[0:15], v[112:115], v[66:69], v[0:15]
	v_pk_add_f32 v[232:233], v[232:233], v[46:47]
	v_pk_add_f32 v[234:235], v[234:235], v[60:61]
	v_mfma_f32_32x32x16_bf16 v[16:31], v[132:135], v[66:69], v[16:31]
	v_cvt_pk_bf16_f32 v66, v56, v57
	v_cvt_pk_bf16_f32 v67, v58, v59
	v_cvt_pk_bf16_f32 v68, v60, v61
	v_cvt_pk_bf16_f32 v69, v62, v63
	v_pk_add_f32 v[234:235], v[234:235], v[62:63]
	v_add_f32_e32 v65, v232, v233
	v_mfma_f32_32x32x16_bf16 v[0:15], v[116:119], v[66:69], v[0:15]
	v_add_f32_e32 v70, v234, v235
	v_add_f32_e32 v65, v65, v70
	v_mfma_f32_32x32x16_bf16 v[16:31], v[128:131], v[66:69], v[16:31]
	v_add_f32_e32 v158, v158, v65
